# SwiGLU K-loop: LDS-DMA pieces per sub-phase rebalanced 2/6/2/6 -> 2/4/4/6 (two pieces of the second load segment issued at the head of the third), second wait vmcnt(6)
# speedup vs baseline: 1.0029x; 1.0029x over previous
; #define PG8_STAGE(bufoff, gbase, voff) do { _Pragma("unroll") for (int _i = 0; _i < 2; ++_i) \
;         __builtin_amdgcn_global_load_lds((const unsigned*)((const char*)(gbase) + (voff)[_i]), (LAS unsigned*)(lds + (bufoff) + ldsw + _i * 8192), 16, 0, 0); } while (0)
; #define PG8_LDA(dst, b, h) do { _Pragma("unroll") for (int m = 0; m < 4; ++m) _Pragma("unroll") for (int k = 0; k < 2; ++k) dst[m][k] = *(const LAS bf16x8*)(lds + PG8_SA(b, h) + aoff + m * 2048 + k * 1024); } while (0)
; #define PG8_LDB(dst, b, h) do { _Pragma("unroll") for (int n = 0; n < 2; ++n) _Pragma("unroll") for (int k = 0; k < 2; ++k) dst[n][k] = *(const LAS bf16x8*)(lds + PG8_SB(b, h) + boff + n * 2048 + k * 1024); } while (0)
; #define PG8_MMA(ai, bj, At, Bt) do { __builtin_amdgcn_s_setprio(1); _Pragma("unroll") for (int m = 0; m < 4; ++m) _Pragma("unroll") for (int n = 0; n < 2; ++n) _Pragma("unroll") for (int k = 0; k < 2; ++k) \
;         acc[ai][bj][m][n] = __builtin_amdgcn_mfma_f32_16x16x32_bf16(Bt[n][k], At[m][k], acc[ai][bj][m][n], 0, 0, 0); __builtin_amdgcn_s_setprio(0); } while (0)
; #define PG8_WAIT_V(n) asm volatile("s_waitcnt vmcnt(" #n ")" ::: "memory")
; #define PG8_WAIT_L(n) asm volatile("s_waitcnt lgkmcnt(" #n ")" ::: "memory")
; #define PG8_BAR __builtin_amdgcn_s_barrier()
; #define PG8_SCHED __builtin_amdgcn_sched_barrier(0)
; template <class Epi, bool ALIGN_EPI = PG8_ALIGN, bool SP2 = PG8_SP2>
; __device__ __forceinline__ void gemm_phase(LAS unsigned char* lds, const Gemm g, const StaticOrder& S, const Epi& E) {
;     ...
;             const bool last = (t == nt - 2);
;             const char* a1 = cA + (size_t)(t + 1) * kstepA;
;             const char* a2 = last ? nA : cA + (size_t)(t + 2) * kstepA; const char* b2 = last ? nB : cB + (size_t)(t + 2) * kstepB;
;             const char* a3 = a2 + kstepA; const char* b3 = b2 + kstepB;
;             if constexpr (SP2) {
;             PG8_LDB(B0, 0, 0); PG8_LDB(B1, 0, 1); PG8_SCHED; PG8_LDA(At, 0, 0); PG8_STAGE(PG8_SA(1, 1), a1 + hstepA, voffA);
;             PG8_WAIT_V(8); PG8_WAIT_L(0); PG8_BAR; PG8_MMA(0, 0, At, B0); PG8_MMA(0, 1, At, B1); PG8_BAR; PG8_SCHED;
;             PG8_LDA(At, 0, 1); PG8_STAGE(PG8_SB(0, 0), b2, voffB); PG8_STAGE(PG8_SB(0, 1), b2 + hstepB, voffB); PG8_STAGE(PG8_SA(0, 0), a2, voffA);
;             PG8_WAIT_V(8); PG8_WAIT_L(0); PG8_BAR; PG8_MMA(1, 0, At, B0); PG8_MMA(1, 1, At, B1); PG8_BAR; PG8_SCHED;
.LBB0_611:
	s_cmp_eq_u32 s47, -2
	s_cbranch_scc1 .Lfirst_iter_u611
	s_add_u32 s22, s20, 0xfffc0080
	s_addc_u32 s23, s21, -1
	s_add_i32 s48, 0, 0x10000
	s_cmp_eq_u32 s47, 12
	s_cselect_b32 s25, s13, s23
	s_cselect_b32 s24, s43, s22
	v_add_u32_e32 v0, s48, v141
	s_cselect_b32 s23, s11, s46
	s_cselect_b32 s22, s44, s45
	s_add_i32 s52, 0, 0x14000
	ds_read_b128 v[144:147], v0
	ds_read_b128 v[148:151], v0 offset:1024
	ds_read_b128 v[152:155], v0 offset:2048
	ds_read_b128 v[156:159], v0 offset:3072
	v_add_u32_e32 v0, s52, v141
	ds_read_b128 v[170:173], v0
	ds_read_b128 v[174:177], v0 offset:1024
	ds_read_b128 v[178:181], v0 offset:2048
	ds_read_b128 v[182:185], v0 offset:3072
	v_lshl_add_u64 v[160:161], s[20:21], 0, v[134:135]
	s_add_i32 m0, s34, 0xc000
	ds_read_b128 v[186:189], v142
	ds_read_b128 v[206:209], v142 offset:1024
	ds_read_b128 v[210:213], v142 offset:2048
	ds_read_b128 v[214:217], v142 offset:3072
	ds_read_b128 v[218:221], v142 offset:4096
	ds_read_b128 v[222:225], v142 offset:5120
	ds_read_b128 v[226:229], v142 offset:6144
	ds_read_b128 v[230:233], v142 offset:7168
	global_load_lds_dwordx4 v[160:161], off
	v_lshl_add_u64 v[160:161], s[20:21], 0, v[136:137]
	s_add_i32 m0, s34, 0xe000
	s_nop 0
	global_load_lds_dwordx4 v[160:161], off
	s_waitcnt vmcnt(8)
	s_waitcnt lgkmcnt(0)
	s_barrier
	s_setprio 1
	s_waitcnt lgkmcnt(0)
	v_mfma_f32_16x16x32_bf16 v[126:129], v[144:147], v[186:189], v[126:129]
	v_mfma_f32_16x16x32_bf16 v[118:121], v[152:155], v[186:189], v[118:121]
	v_mfma_f32_16x16x32_bf16 v[110:113], v[144:147], v[210:213], v[110:113]
	v_mfma_f32_16x16x32_bf16 v[102:105], v[152:155], v[210:213], v[102:105]
	v_mfma_f32_16x16x32_bf16 v[94:97], v[144:147], v[218:221], v[94:97]
	v_mfma_f32_16x16x32_bf16 v[86:89], v[152:155], v[218:221], v[86:89]
	v_mfma_f32_16x16x32_bf16 v[78:81], v[144:147], v[226:229], v[78:81]
	v_mfma_f32_16x16x32_bf16 v[70:73], v[152:155], v[226:229], v[70:73]
	v_mfma_f32_16x16x32_bf16 v[126:129], v[148:151], v[206:209], v[126:129]
	v_mfma_f32_16x16x32_bf16 v[118:121], v[156:159], v[206:209], v[118:121]
	v_mfma_f32_16x16x32_bf16 v[110:113], v[148:151], v[214:217], v[110:113]
	v_mfma_f32_16x16x32_bf16 v[102:105], v[156:159], v[214:217], v[102:105]
	v_mfma_f32_16x16x32_bf16 v[94:97], v[148:151], v[222:225], v[94:97]
	v_mfma_f32_16x16x32_bf16 v[86:89], v[156:159], v[222:225], v[86:89]
	v_mfma_f32_16x16x32_bf16 v[78:81], v[148:151], v[230:233], v[78:81]
	v_mfma_f32_16x16x32_bf16 v[70:73], v[156:159], v[230:233], v[70:73]
	s_setprio 0
	s_setprio 1
	v_mfma_f32_16x16x32_bf16 v[122:125], v[170:173], v[186:189], v[122:125]
	v_mfma_f32_16x16x32_bf16 v[114:117], v[178:181], v[186:189], v[114:117]
	v_mfma_f32_16x16x32_bf16 v[106:109], v[170:173], v[210:213], v[106:109]
	v_mfma_f32_16x16x32_bf16 v[98:101], v[178:181], v[210:213], v[98:101]
	v_mfma_f32_16x16x32_bf16 v[90:93], v[170:173], v[218:221], v[90:93]
	v_mfma_f32_16x16x32_bf16 v[82:85], v[178:181], v[218:221], v[82:85]
	v_mfma_f32_16x16x32_bf16 v[74:77], v[170:173], v[226:229], v[74:77]
	v_mfma_f32_16x16x32_bf16 v[66:69], v[178:181], v[226:229], v[66:69]
	v_mfma_f32_16x16x32_bf16 v[122:125], v[174:177], v[206:209], v[122:125]
	v_mfma_f32_16x16x32_bf16 v[114:117], v[182:185], v[206:209], v[114:117]
	v_mfma_f32_16x16x32_bf16 v[106:109], v[174:177], v[214:217], v[106:109]
	v_mfma_f32_16x16x32_bf16 v[98:101], v[182:185], v[214:217], v[98:101]
	v_mfma_f32_16x16x32_bf16 v[90:93], v[174:177], v[222:225], v[90:93]
	v_mfma_f32_16x16x32_bf16 v[82:85], v[182:185], v[222:225], v[82:85]
	v_mfma_f32_16x16x32_bf16 v[74:77], v[174:177], v[230:233], v[74:77]
	v_mfma_f32_16x16x32_bf16 v[66:69], v[182:185], v[230:233], v[66:69]
	s_setprio 0
	s_barrier
	s_add_i32 s48, s48, s33
	v_lshl_add_u64 v[160:161], s[22:23], 0, v[130:131]
	s_mov_b32 m0, s48
	ds_read_b128 v[186:189], v142 offset:16384
	ds_read_b128 v[206:209], v142 offset:17408
	ds_read_b128 v[210:213], v142 offset:18432
	ds_read_b128 v[214:217], v142 offset:19456
	ds_read_b128 v[218:221], v142 offset:20480
	ds_read_b128 v[222:225], v142 offset:21504
	ds_read_b128 v[226:229], v142 offset:22528
	ds_read_b128 v[230:233], v142 offset:23552
	global_load_lds_dwordx4 v[160:161], off
	s_add_i32 m0, s48, 0x2000
	s_add_u32 s48, s22, 0x40000
	v_lshl_add_u64 v[164:165], s[22:23], 0, v[132:133]
	s_addc_u32 s49, s23, 0
	s_add_i32 s52, s52, s33
	global_load_lds_dwordx4 v[164:165], off
	v_lshl_add_u64 v[166:167], s[48:49], 0, v[130:131]
	s_mov_b32 m0, s52
	v_lshl_add_u64 v[194:195], s[24:25], 0, v[132:133]
	global_load_lds_dwordx4 v[166:167], off
	v_lshl_add_u64 v[166:167], s[48:49], 0, v[132:133]
	s_add_i32 m0, s52, 0x2000
	s_nop 0
	global_load_lds_dwordx4 v[166:167], off
	s_waitcnt vmcnt(6)
	s_waitcnt lgkmcnt(0)
	s_barrier
; #define PG8_STAGE(bufoff, gbase, voff) do { _Pragma("unroll") for (int _i = 0; _i < 2; ++_i) \
;         __builtin_amdgcn_global_load_lds((const unsigned*)((const char*)(gbase) + (voff)[_i]), (LAS unsigned*)(lds + (bufoff) + ldsw + _i * 8192), 16, 0, 0); } while (0)
; #define PG8_LDA(dst, b, h) do { _Pragma("unroll") for (int m = 0; m < 4; ++m) _Pragma("unroll") for (int k = 0; k < 2; ++k) dst[m][k] = *(const LAS bf16x8*)(lds + PG8_SA(b, h) + aoff + m * 2048 + k * 1024); } while (0)
; #define PG8_LDB(dst, b, h) do { _Pragma("unroll") for (int n = 0; n < 2; ++n) _Pragma("unroll") for (int k = 0; k < 2; ++k) dst[n][k] = *(const LAS bf16x8*)(lds + PG8_SB(b, h) + boff + n * 2048 + k * 1024); } while (0)
; #define PG8_MMA(ai, bj, At, Bt) do { __builtin_amdgcn_s_setprio(1); _Pragma("unroll") for (int m = 0; m < 4; ++m) _Pragma("unroll") for (int n = 0; n < 2; ++n) _Pragma("unroll") for (int k = 0; k < 2; ++k) \
;         acc[ai][bj][m][n] = __builtin_amdgcn_mfma_f32_16x16x32_bf16(Bt[n][k], At[m][k], acc[ai][bj][m][n], 0, 0, 0); __builtin_amdgcn_s_setprio(0); } while (0)
; #define PG8_WAIT_V(n) asm volatile("s_waitcnt vmcnt(" #n ")" ::: "memory")
; #define PG8_WAIT_L(n) asm volatile("s_waitcnt lgkmcnt(" #n ")" ::: "memory")
; #define PG8_BAR __builtin_amdgcn_s_barrier()
; #define PG8_SCHED __builtin_amdgcn_sched_barrier(0)
; template <class Epi, bool ALIGN_EPI = PG8_ALIGN, bool SP2 = PG8_SP2>
; __device__ __forceinline__ void gemm_phase(LAS unsigned char* lds, const Gemm g, const StaticOrder& S, const Epi& E) {
;     ...
;             PG8_WAIT_V(8); PG8_WAIT_L(0); PG8_BAR; PG8_MMA(1, 0, At, B0); PG8_MMA(1, 1, At, B1); PG8_BAR; PG8_SCHED;
;             PG8_LDB(B0, 1, 0); PG8_LDB(B1, 1, 1); PG8_SCHED; PG8_LDA(At, 1, 0); PG8_STAGE(PG8_SA(0, 1), a2 + hstepA, voffA);
;             PG8_WAIT_V(8); PG8_WAIT_L(0); PG8_BAR; PG8_MMA(0, 0, At, B0); PG8_MMA(0, 1, At, B1); PG8_BAR; PG8_SCHED;
	s_setprio 1
	s_waitcnt lgkmcnt(0)
	v_mfma_f32_16x16x32_bf16 v[62:65], v[144:147], v[186:189], v[62:65]
	v_mfma_f32_16x16x32_bf16 v[54:57], v[152:155], v[186:189], v[54:57]
	v_mfma_f32_16x16x32_bf16 v[46:49], v[144:147], v[210:213], v[46:49]
	v_mfma_f32_16x16x32_bf16 v[38:41], v[152:155], v[210:213], v[38:41]
	v_mfma_f32_16x16x32_bf16 v[30:33], v[144:147], v[218:221], v[30:33]
	v_mfma_f32_16x16x32_bf16 v[22:25], v[152:155], v[218:221], v[22:25]
	v_mfma_f32_16x16x32_bf16 v[14:17], v[144:147], v[226:229], v[14:17]
	v_mfma_f32_16x16x32_bf16 v[6:9], v[152:155], v[226:229], v[6:9]
	v_mfma_f32_16x16x32_bf16 v[62:65], v[148:151], v[206:209], v[62:65]
	v_mfma_f32_16x16x32_bf16 v[54:57], v[156:159], v[206:209], v[54:57]
	v_mfma_f32_16x16x32_bf16 v[46:49], v[148:151], v[214:217], v[46:49]
	v_mfma_f32_16x16x32_bf16 v[38:41], v[156:159], v[214:217], v[38:41]
	v_mfma_f32_16x16x32_bf16 v[30:33], v[148:151], v[222:225], v[30:33]
	v_mfma_f32_16x16x32_bf16 v[22:25], v[156:159], v[222:225], v[22:25]
	v_mfma_f32_16x16x32_bf16 v[14:17], v[148:151], v[230:233], v[14:17]
	v_mfma_f32_16x16x32_bf16 v[6:9], v[156:159], v[230:233], v[6:9]
	s_setprio 0
	s_setprio 1
	v_mfma_f32_16x16x32_bf16 v[58:61], v[170:173], v[186:189], v[58:61]
	v_mfma_f32_16x16x32_bf16 v[50:53], v[178:181], v[186:189], v[50:53]
	v_mfma_f32_16x16x32_bf16 v[42:45], v[170:173], v[210:213], v[42:45]
	v_mfma_f32_16x16x32_bf16 v[34:37], v[178:181], v[210:213], v[34:37]
	v_mfma_f32_16x16x32_bf16 v[26:29], v[170:173], v[218:221], v[26:29]
	v_mfma_f32_16x16x32_bf16 v[18:21], v[178:181], v[218:221], v[18:21]
	v_mfma_f32_16x16x32_bf16 v[10:13], v[170:173], v[226:229], v[10:13]
	v_mfma_f32_16x16x32_bf16 v[2:5], v[178:181], v[226:229], v[2:5]
	v_mfma_f32_16x16x32_bf16 v[58:61], v[174:177], v[206:209], v[58:61]
	v_mfma_f32_16x16x32_bf16 v[50:53], v[182:185], v[206:209], v[50:53]
	v_mfma_f32_16x16x32_bf16 v[42:45], v[174:177], v[214:217], v[42:45]
	v_mfma_f32_16x16x32_bf16 v[34:37], v[182:185], v[214:217], v[34:37]
	v_mfma_f32_16x16x32_bf16 v[26:29], v[174:177], v[222:225], v[26:29]
	v_mfma_f32_16x16x32_bf16 v[18:21], v[182:185], v[222:225], v[18:21]
	v_mfma_f32_16x16x32_bf16 v[10:13], v[174:177], v[230:233], v[10:13]
	v_mfma_f32_16x16x32_bf16 v[2:5], v[182:185], v[230:233], v[2:5]
	s_setprio 0
	s_barrier
	s_add_i32 s48, 0, 0x18000
	v_add_u32_e32 v0, s48, v141
	s_add_i32 s49, 0, 0x1c000
	ds_read_b128 v[144:147], v0
	ds_read_b128 v[148:151], v0 offset:1024
	ds_read_b128 v[152:155], v0 offset:2048
	ds_read_b128 v[156:159], v0 offset:3072
	v_add_u32_e32 v0, s49, v141
	ds_read_b128 v[170:173], v0
	ds_read_b128 v[174:177], v0 offset:1024
	ds_read_b128 v[178:181], v0 offset:2048
	ds_read_b128 v[182:185], v0 offset:3072
	v_lshl_add_u64 v[166:167], s[24:25], 0, v[130:131]
	s_mov_b32 m0, s34
	s_nop 0
	global_load_lds_dwordx4 v[166:167], off
	s_mov_b32 m0, s35
	s_nop 0
	global_load_lds_dwordx4 v[194:195], off
	s_add_u32 s24, s24, 0x40000
	s_addc_u32 s25, s25, 0
	s_mov_b32 m0, s36
	v_lshl_add_u64 v[196:197], s[24:25], 0, v[130:131]
	ds_read_b128 v[186:189], v142 offset:32768
	ds_read_b128 v[206:209], v142 offset:33792
	ds_read_b128 v[210:213], v142 offset:34816
	ds_read_b128 v[214:217], v142 offset:35840
	ds_read_b128 v[218:221], v142 offset:36864
	ds_read_b128 v[222:225], v142 offset:37888
	ds_read_b128 v[226:229], v142 offset:38912
	ds_read_b128 v[230:233], v142 offset:39936
	global_load_lds_dwordx4 v[196:197], off
	v_lshl_add_u64 v[196:197], s[24:25], 0, v[132:133]
	s_mov_b32 m0, s37
	s_nop 0
	global_load_lds_dwordx4 v[196:197], off
	s_waitcnt vmcnt(8)
	s_waitcnt lgkmcnt(0)
	s_barrier
	s_setprio 1
	s_waitcnt lgkmcnt(0)
	v_mfma_f32_16x16x32_bf16 v[126:129], v[144:147], v[186:189], v[126:129]
	v_mfma_f32_16x16x32_bf16 v[118:121], v[152:155], v[186:189], v[118:121]
	v_mfma_f32_16x16x32_bf16 v[110:113], v[144:147], v[210:213], v[110:113]
	v_mfma_f32_16x16x32_bf16 v[102:105], v[152:155], v[210:213], v[102:105]
	v_mfma_f32_16x16x32_bf16 v[94:97], v[144:147], v[218:221], v[94:97]
	v_mfma_f32_16x16x32_bf16 v[86:89], v[152:155], v[218:221], v[86:89]
	v_mfma_f32_16x16x32_bf16 v[78:81], v[144:147], v[226:229], v[78:81]
	v_mfma_f32_16x16x32_bf16 v[70:73], v[152:155], v[226:229], v[70:73]
	v_mfma_f32_16x16x32_bf16 v[126:129], v[148:151], v[206:209], v[126:129]
	v_mfma_f32_16x16x32_bf16 v[118:121], v[156:159], v[206:209], v[118:121]
	v_mfma_f32_16x16x32_bf16 v[110:113], v[148:151], v[214:217], v[110:113]
	v_mfma_f32_16x16x32_bf16 v[102:105], v[156:159], v[214:217], v[102:105]
	v_mfma_f32_16x16x32_bf16 v[94:97], v[148:151], v[222:225], v[94:97]
	v_mfma_f32_16x16x32_bf16 v[86:89], v[156:159], v[222:225], v[86:89]
	v_mfma_f32_16x16x32_bf16 v[78:81], v[148:151], v[230:233], v[78:81]
	v_mfma_f32_16x16x32_bf16 v[70:73], v[156:159], v[230:233], v[70:73]
	s_setprio 0
	s_setprio 1
	v_mfma_f32_16x16x32_bf16 v[122:125], v[170:173], v[186:189], v[122:125]
	v_mfma_f32_16x16x32_bf16 v[114:117], v[178:181], v[186:189], v[114:117]
	v_mfma_f32_16x16x32_bf16 v[106:109], v[170:173], v[210:213], v[106:109]
	v_mfma_f32_16x16x32_bf16 v[98:101], v[178:181], v[210:213], v[98:101]
	v_mfma_f32_16x16x32_bf16 v[90:93], v[170:173], v[218:221], v[90:93]
	v_mfma_f32_16x16x32_bf16 v[82:85], v[178:181], v[218:221], v[82:85]
	v_mfma_f32_16x16x32_bf16 v[74:77], v[170:173], v[226:229], v[74:77]
	v_mfma_f32_16x16x32_bf16 v[66:69], v[178:181], v[226:229], v[66:69]
	v_mfma_f32_16x16x32_bf16 v[122:125], v[174:177], v[206:209], v[122:125]
	v_mfma_f32_16x16x32_bf16 v[114:117], v[182:185], v[206:209], v[114:117]
	v_mfma_f32_16x16x32_bf16 v[106:109], v[174:177], v[214:217], v[106:109]
	v_mfma_f32_16x16x32_bf16 v[98:101], v[182:185], v[214:217], v[98:101]
	v_mfma_f32_16x16x32_bf16 v[90:93], v[174:177], v[222:225], v[90:93]
	v_mfma_f32_16x16x32_bf16 v[82:85], v[182:185], v[222:225], v[82:85]
	v_mfma_f32_16x16x32_bf16 v[74:77], v[174:177], v[230:233], v[74:77]
	v_mfma_f32_16x16x32_bf16 v[66:69], v[182:185], v[230:233], v[66:69]
	s_setprio 0
	s_barrier
; #define PG8_STAGE(bufoff, gbase, voff) do { _Pragma("unroll") for (int _i = 0; _i < 2; ++_i) \
;         __builtin_amdgcn_global_load_lds((const unsigned*)((const char*)(gbase) + (voff)[_i]), (LAS unsigned*)(lds + (bufoff) + ldsw + _i * 8192), 16, 0, 0); } while (0)
; #define PG8_LDA(dst, b, h) do { _Pragma("unroll") for (int m = 0; m < 4; ++m) _Pragma("unroll") for (int k = 0; k < 2; ++k) dst[m][k] = *(const LAS bf16x8*)(lds + PG8_SA(b, h) + aoff + m * 2048 + k * 1024); } while (0)
; #define PG8_MMA(ai, bj, At, Bt) do { __builtin_amdgcn_s_setprio(1); _Pragma("unroll") for (int m = 0; m < 4; ++m) _Pragma("unroll") for (int n = 0; n < 2; ++n) _Pragma("unroll") for (int k = 0; k < 2; ++k) \
;         acc[ai][bj][m][n] = __builtin_amdgcn_mfma_f32_16x16x32_bf16(Bt[n][k], At[m][k], acc[ai][bj][m][n], 0, 0, 0); __builtin_amdgcn_s_setprio(0); } while (0)
; #define PG8_WAIT_V(n) asm volatile("s_waitcnt vmcnt(" #n ")" ::: "memory")
; #define PG8_WAIT_L(n) asm volatile("s_waitcnt lgkmcnt(" #n ")" ::: "memory")
; #define PG8_BAR __builtin_amdgcn_s_barrier()
; #define PG8_SCHED __builtin_amdgcn_sched_barrier(0)
; template <class Epi, bool ALIGN_EPI = PG8_ALIGN, bool SP2 = PG8_SP2>
; __device__ __forceinline__ void gemm_phase(LAS unsigned char* lds, const Gemm g, const StaticOrder& S, const Epi& E) {
;     ...
;             PG8_LDA(At, 1, 1); PG8_STAGE(PG8_SB(1, 0), b3, voffB); PG8_STAGE(PG8_SB(1, 1), b3 + hstepB, voffB); PG8_STAGE(PG8_SA(1, 0), a3, voffA);
;             PG8_WAIT_V(8); PG8_WAIT_L(0); PG8_BAR; PG8_MMA(1, 0, At, B0); PG8_MMA(1, 1, At, B1); PG8_BAR; PG8_SCHED;
	s_add_i32 s24, s48, s33
	v_lshl_add_u64 v[160:161], v[160:161], 0, s[50:51]
	s_mov_b32 m0, s24
	ds_read_b128 v[186:189], v142 offset:49152
	ds_read_b128 v[206:209], v142 offset:50176
	ds_read_b128 v[210:213], v142 offset:51200
	ds_read_b128 v[214:217], v142 offset:52224
	ds_read_b128 v[218:221], v142 offset:53248
	ds_read_b128 v[222:225], v142 offset:54272
	ds_read_b128 v[226:229], v142 offset:55296
	ds_read_b128 v[230:233], v142 offset:56320
	global_load_lds_dwordx4 v[160:161], off
	s_add_i32 m0, s24, 0x2000
	s_add_u32 s22, s22, 0x40080
	v_lshl_add_u64 v[160:161], v[164:165], 0, s[50:51]
	s_addc_u32 s23, s23, 0
	s_add_i32 s24, s49, s33
	global_load_lds_dwordx4 v[160:161], off
	v_lshl_add_u64 v[160:161], s[22:23], 0, v[130:131]
	s_mov_b32 m0, s24
	s_nop 0
	global_load_lds_dwordx4 v[160:161], off
	v_lshl_add_u64 v[160:161], s[22:23], 0, v[132:133]
	s_add_i32 m0, s24, 0x2000
	s_nop 0
	global_load_lds_dwordx4 v[160:161], off
	v_lshl_add_u64 v[160:161], v[166:167], 0, s[50:51]
	s_mov_b32 m0, s40
	s_nop 0
	global_load_lds_dwordx4 v[160:161], off
	v_lshl_add_u64 v[160:161], v[194:195], 0, s[50:51]
	s_mov_b32 m0, s41
	s_nop 0
	global_load_lds_dwordx4 v[160:161], off
	s_waitcnt vmcnt(8)
	s_waitcnt lgkmcnt(0)
	s_barrier
	s_setprio 1
	s_waitcnt lgkmcnt(0)
	v_mfma_f32_16x16x32_bf16 v[62:65], v[144:147], v[186:189], v[62:65]
	v_mfma_f32_16x16x32_bf16 v[54:57], v[152:155], v[186:189], v[54:57]
	v_mfma_f32_16x16x32_bf16 v[46:49], v[144:147], v[210:213], v[46:49]
	v_mfma_f32_16x16x32_bf16 v[38:41], v[152:155], v[210:213], v[38:41]
	v_mfma_f32_16x16x32_bf16 v[30:33], v[144:147], v[218:221], v[30:33]
	v_mfma_f32_16x16x32_bf16 v[22:25], v[152:155], v[218:221], v[22:25]
	v_mfma_f32_16x16x32_bf16 v[14:17], v[144:147], v[226:229], v[14:17]
	v_mfma_f32_16x16x32_bf16 v[6:9], v[152:155], v[226:229], v[6:9]
	v_mfma_f32_16x16x32_bf16 v[62:65], v[148:151], v[206:209], v[62:65]
	v_mfma_f32_16x16x32_bf16 v[54:57], v[156:159], v[206:209], v[54:57]
	v_mfma_f32_16x16x32_bf16 v[46:49], v[148:151], v[214:217], v[46:49]
	v_mfma_f32_16x16x32_bf16 v[38:41], v[156:159], v[214:217], v[38:41]
	v_mfma_f32_16x16x32_bf16 v[30:33], v[148:151], v[222:225], v[30:33]
	v_mfma_f32_16x16x32_bf16 v[22:25], v[156:159], v[222:225], v[22:25]
	v_mfma_f32_16x16x32_bf16 v[14:17], v[148:151], v[230:233], v[14:17]
	v_mfma_f32_16x16x32_bf16 v[6:9], v[156:159], v[230:233], v[6:9]
	s_setprio 0
	s_setprio 1
	v_mfma_f32_16x16x32_bf16 v[58:61], v[170:173], v[186:189], v[58:61]
	v_mfma_f32_16x16x32_bf16 v[50:53], v[178:181], v[186:189], v[50:53]
	v_mfma_f32_16x16x32_bf16 v[42:45], v[170:173], v[210:213], v[42:45]
	v_mfma_f32_16x16x32_bf16 v[34:37], v[178:181], v[210:213], v[34:37]
	v_mfma_f32_16x16x32_bf16 v[26:29], v[170:173], v[218:221], v[26:29]
	v_mfma_f32_16x16x32_bf16 v[18:21], v[178:181], v[218:221], v[18:21]
	v_mfma_f32_16x16x32_bf16 v[10:13], v[170:173], v[226:229], v[10:13]
	v_mfma_f32_16x16x32_bf16 v[2:5], v[178:181], v[226:229], v[2:5]
	v_mfma_f32_16x16x32_bf16 v[58:61], v[174:177], v[206:209], v[58:61]
	v_mfma_f32_16x16x32_bf16 v[50:53], v[182:185], v[206:209], v[50:53]
	v_mfma_f32_16x16x32_bf16 v[42:45], v[174:177], v[214:217], v[42:45]
	v_mfma_f32_16x16x32_bf16 v[34:37], v[182:185], v[214:217], v[34:37]
	v_mfma_f32_16x16x32_bf16 v[26:29], v[174:177], v[222:225], v[26:29]
	v_mfma_f32_16x16x32_bf16 v[18:21], v[182:185], v[222:225], v[18:21]
	v_mfma_f32_16x16x32_bf16 v[10:13], v[174:177], v[230:233], v[10:13]
	v_mfma_f32_16x16x32_bf16 v[2:5], v[182:185], v[230:233], v[2:5]
	s_setprio 0
	s_barrier
	s_add_i32 s47, s47, 2
	s_add_u32 s20, s20, 0x100
	s_addc_u32 s21, s21, 0
	s_add_u32 s45, s45, 0x100
	s_addc_u32 s46, s46, 0
	s_cmp_gt_u32 s47, 13
	s_cbranch_scc0 .LBB0_611
	s_and_b64 vcc, exec, s[8:9]
	s_cbranch_vccz .LBB0_614
	s_barrier

; #define PG8_STAGE(bufoff, gbase, voff) do { _Pragma("unroll") for (int _i = 0; _i < 2; ++_i) \
;         __builtin_amdgcn_global_load_lds((const unsigned*)((const char*)(gbase) + (voff)[_i]), (LAS unsigned*)(lds + (bufoff) + ldsw + _i * 8192), 16, 0, 0); } while (0)
; #define PG8_LDA(dst, b, h) do { _Pragma("unroll") for (int m = 0; m < 4; ++m) _Pragma("unroll") for (int k = 0; k < 2; ++k) dst[m][k] = *(const LAS bf16x8*)(lds + PG8_SA(b, h) + aoff + m * 2048 + k * 1024); } while (0)
; #define PG8_LDB(dst, b, h) do { _Pragma("unroll") for (int n = 0; n < 2; ++n) _Pragma("unroll") for (int k = 0; k < 2; ++k) dst[n][k] = *(const LAS bf16x8*)(lds + PG8_SB(b, h) + boff + n * 2048 + k * 1024); } while (0)
; #define PG8_MMA(ai, bj, At, Bt) do { __builtin_amdgcn_s_setprio(1); _Pragma("unroll") for (int m = 0; m < 4; ++m) _Pragma("unroll") for (int n = 0; n < 2; ++n) _Pragma("unroll") for (int k = 0; k < 2; ++k) \
;         acc[ai][bj][m][n] = __builtin_amdgcn_mfma_f32_16x16x32_bf16(Bt[n][k], At[m][k], acc[ai][bj][m][n], 0, 0, 0); __builtin_amdgcn_s_setprio(0); } while (0)
; #define PG8_WAIT_V(n) asm volatile("s_waitcnt vmcnt(" #n ")" ::: "memory")
; #define PG8_WAIT_L(n) asm volatile("s_waitcnt lgkmcnt(" #n ")" ::: "memory")
; #define PG8_BAR __builtin_amdgcn_s_barrier()
; #define PG8_SCHED __builtin_amdgcn_sched_barrier(0)
; template <class Epi, bool ALIGN_EPI = PG8_ALIGN, bool SP2 = PG8_SP2>
; __device__ __forceinline__ void gemm_phase(LAS unsigned char* lds, const Gemm g, const StaticOrder& S, const Epi& E) {
;     ...
;             const bool last = (t == nt - 2);
;             const char* a1 = cA + (size_t)(t + 1) * kstepA;
;             const char* a2 = last ? nA : cA + (size_t)(t + 2) * kstepA; const char* b2 = last ? nB : cB + (size_t)(t + 2) * kstepB;
;             const char* a3 = a2 + kstepA; const char* b3 = b2 + kstepB;
;             if constexpr (SP2) {
;             PG8_LDB(B0, 0, 0); PG8_LDB(B1, 0, 1); PG8_SCHED; PG8_LDA(At, 0, 0); PG8_STAGE(PG8_SA(1, 1), a1 + hstepA, voffA);
;             PG8_WAIT_V(8); PG8_WAIT_L(0); PG8_BAR; PG8_MMA(0, 0, At, B0); PG8_MMA(0, 1, At, B1); PG8_BAR; PG8_SCHED;
;             PG8_LDA(At, 0, 1); PG8_STAGE(PG8_SB(0, 0), b2, voffB); PG8_STAGE(PG8_SB(0, 1), b2 + hstepB, voffB); PG8_STAGE(PG8_SA(0, 0), a2, voffA);
;             PG8_WAIT_V(8); PG8_WAIT_L(0); PG8_BAR; PG8_MMA(1, 0, At, B0); PG8_MMA(1, 1, At, B1); PG8_BAR; PG8_SCHED;
.Lfirst_iter_u611:
	s_add_u32 s22, s20, 0xfffc0080
	s_addc_u32 s23, s21, -1
	s_add_i32 s48, 0, 0x10000
	s_cmp_eq_u32 s47, 12
	s_cselect_b32 s25, s13, s23
	s_cselect_b32 s24, s43, s22
	v_add_u32_e32 v0, s48, v141
	s_cselect_b32 s23, s11, s46
	s_cselect_b32 s22, s44, s45
	s_add_i32 s52, 0, 0x14000
	ds_read_b128 v[144:147], v0
	ds_read_b128 v[148:151], v0 offset:1024
	ds_read_b128 v[152:155], v0 offset:2048
	ds_read_b128 v[156:159], v0 offset:3072
	v_add_u32_e32 v0, s52, v141
	ds_read_b128 v[170:173], v0
	ds_read_b128 v[174:177], v0 offset:1024
	ds_read_b128 v[178:181], v0 offset:2048
	ds_read_b128 v[182:185], v0 offset:3072
	v_lshl_add_u64 v[160:161], s[20:21], 0, v[134:135]
	s_add_i32 m0, s34, 0xc000
	ds_read_b128 v[186:189], v142
	ds_read_b128 v[206:209], v142 offset:1024
	ds_read_b128 v[210:213], v142 offset:2048
	ds_read_b128 v[214:217], v142 offset:3072
	ds_read_b128 v[218:221], v142 offset:4096
	ds_read_b128 v[222:225], v142 offset:5120
	ds_read_b128 v[226:229], v142 offset:6144
	ds_read_b128 v[230:233], v142 offset:7168
	global_load_lds_dwordx4 v[160:161], off
	v_lshl_add_u64 v[160:161], s[20:21], 0, v[136:137]
	s_add_i32 m0, s34, 0xe000
	s_nop 0
	global_load_lds_dwordx4 v[160:161], off
	s_waitcnt vmcnt(8)
	s_waitcnt lgkmcnt(0)
	s_barrier
	s_setprio 1
	s_waitcnt lgkmcnt(0)
	v_mfma_f32_16x16x32_bf16 v[126:129], v[144:147], v[186:189], 0
	v_mfma_f32_16x16x32_bf16 v[118:121], v[152:155], v[186:189], 0
	v_mfma_f32_16x16x32_bf16 v[110:113], v[144:147], v[210:213], 0
	v_mfma_f32_16x16x32_bf16 v[102:105], v[152:155], v[210:213], 0
	v_mfma_f32_16x16x32_bf16 v[94:97], v[144:147], v[218:221], 0
	v_mfma_f32_16x16x32_bf16 v[86:89], v[152:155], v[218:221], 0
	v_mfma_f32_16x16x32_bf16 v[78:81], v[144:147], v[226:229], 0
	v_mfma_f32_16x16x32_bf16 v[70:73], v[152:155], v[226:229], 0
	v_mfma_f32_16x16x32_bf16 v[126:129], v[148:151], v[206:209], v[126:129]
	v_mfma_f32_16x16x32_bf16 v[118:121], v[156:159], v[206:209], v[118:121]
	v_mfma_f32_16x16x32_bf16 v[110:113], v[148:151], v[214:217], v[110:113]
	v_mfma_f32_16x16x32_bf16 v[102:105], v[156:159], v[214:217], v[102:105]
	v_mfma_f32_16x16x32_bf16 v[94:97], v[148:151], v[222:225], v[94:97]
	v_mfma_f32_16x16x32_bf16 v[86:89], v[156:159], v[222:225], v[86:89]
	v_mfma_f32_16x16x32_bf16 v[78:81], v[148:151], v[230:233], v[78:81]
	v_mfma_f32_16x16x32_bf16 v[70:73], v[156:159], v[230:233], v[70:73]
	s_setprio 0
	s_setprio 1
	v_mfma_f32_16x16x32_bf16 v[122:125], v[170:173], v[186:189], 0
	v_mfma_f32_16x16x32_bf16 v[114:117], v[178:181], v[186:189], 0
	v_mfma_f32_16x16x32_bf16 v[106:109], v[170:173], v[210:213], 0
	v_mfma_f32_16x16x32_bf16 v[98:101], v[178:181], v[210:213], 0
	v_mfma_f32_16x16x32_bf16 v[90:93], v[170:173], v[218:221], 0
	v_mfma_f32_16x16x32_bf16 v[82:85], v[178:181], v[218:221], 0
	v_mfma_f32_16x16x32_bf16 v[74:77], v[170:173], v[226:229], 0
	v_mfma_f32_16x16x32_bf16 v[66:69], v[178:181], v[226:229], 0
	v_mfma_f32_16x16x32_bf16 v[122:125], v[174:177], v[206:209], v[122:125]
	v_mfma_f32_16x16x32_bf16 v[114:117], v[182:185], v[206:209], v[114:117]
	v_mfma_f32_16x16x32_bf16 v[106:109], v[174:177], v[214:217], v[106:109]
	v_mfma_f32_16x16x32_bf16 v[98:101], v[182:185], v[214:217], v[98:101]
	v_mfma_f32_16x16x32_bf16 v[90:93], v[174:177], v[222:225], v[90:93]
	v_mfma_f32_16x16x32_bf16 v[82:85], v[182:185], v[222:225], v[82:85]
	v_mfma_f32_16x16x32_bf16 v[74:77], v[174:177], v[230:233], v[74:77]
	v_mfma_f32_16x16x32_bf16 v[66:69], v[182:185], v[230:233], v[66:69]
	s_setprio 0
	s_barrier
	s_add_i32 s48, s48, s33
	v_lshl_add_u64 v[160:161], s[22:23], 0, v[130:131]
	s_mov_b32 m0, s48
	ds_read_b128 v[186:189], v142 offset:16384
	ds_read_b128 v[206:209], v142 offset:17408
	ds_read_b128 v[210:213], v142 offset:18432
	ds_read_b128 v[214:217], v142 offset:19456
	ds_read_b128 v[218:221], v142 offset:20480
	ds_read_b128 v[222:225], v142 offset:21504
	ds_read_b128 v[226:229], v142 offset:22528
	ds_read_b128 v[230:233], v142 offset:23552
	global_load_lds_dwordx4 v[160:161], off
	s_add_i32 m0, s48, 0x2000
	s_add_u32 s48, s22, 0x40000
	v_lshl_add_u64 v[164:165], s[22:23], 0, v[132:133]
	s_addc_u32 s49, s23, 0
	s_add_i32 s52, s52, s33
	global_load_lds_dwordx4 v[164:165], off
	v_lshl_add_u64 v[166:167], s[48:49], 0, v[130:131]
	s_mov_b32 m0, s52
	v_lshl_add_u64 v[194:195], s[24:25], 0, v[132:133]
	global_load_lds_dwordx4 v[166:167], off
	v_lshl_add_u64 v[166:167], s[48:49], 0, v[132:133]
	s_add_i32 m0, s52, 0x2000
	s_nop 0
	global_load_lds_dwordx4 v[166:167], off
	s_waitcnt vmcnt(6)
	s_waitcnt lgkmcnt(0)
	s_barrier
	s_setprio 1
	s_waitcnt lgkmcnt(0)
	v_mfma_f32_16x16x32_bf16 v[62:65], v[144:147], v[186:189], 0
	v_mfma_f32_16x16x32_bf16 v[54:57], v[152:155], v[186:189], 0
	v_mfma_f32_16x16x32_bf16 v[46:49], v[144:147], v[210:213], 0
	v_mfma_f32_16x16x32_bf16 v[38:41], v[152:155], v[210:213], 0
	v_mfma_f32_16x16x32_bf16 v[30:33], v[144:147], v[218:221], 0
	v_mfma_f32_16x16x32_bf16 v[22:25], v[152:155], v[218:221], 0
	v_mfma_f32_16x16x32_bf16 v[14:17], v[144:147], v[226:229], 0
	v_mfma_f32_16x16x32_bf16 v[6:9], v[152:155], v[226:229], 0
	v_mfma_f32_16x16x32_bf16 v[62:65], v[148:151], v[206:209], v[62:65]
	v_mfma_f32_16x16x32_bf16 v[54:57], v[156:159], v[206:209], v[54:57]
	v_mfma_f32_16x16x32_bf16 v[46:49], v[148:151], v[214:217], v[46:49]
	v_mfma_f32_16x16x32_bf16 v[38:41], v[156:159], v[214:217], v[38:41]
	v_mfma_f32_16x16x32_bf16 v[30:33], v[148:151], v[222:225], v[30:33]
	v_mfma_f32_16x16x32_bf16 v[22:25], v[156:159], v[222:225], v[22:25]
	v_mfma_f32_16x16x32_bf16 v[14:17], v[148:151], v[230:233], v[14:17]
	v_mfma_f32_16x16x32_bf16 v[6:9], v[156:159], v[230:233], v[6:9]
	s_setprio 0
	s_setprio 1
	v_mfma_f32_16x16x32_bf16 v[58:61], v[170:173], v[186:189], 0
	v_mfma_f32_16x16x32_bf16 v[50:53], v[178:181], v[186:189], 0
	v_mfma_f32_16x16x32_bf16 v[42:45], v[170:173], v[210:213], 0
	v_mfma_f32_16x16x32_bf16 v[34:37], v[178:181], v[210:213], 0
	v_mfma_f32_16x16x32_bf16 v[26:29], v[170:173], v[218:221], 0
	v_mfma_f32_16x16x32_bf16 v[18:21], v[178:181], v[218:221], 0
	v_mfma_f32_16x16x32_bf16 v[10:13], v[170:173], v[226:229], 0
	v_mfma_f32_16x16x32_bf16 v[2:5], v[178:181], v[226:229], 0
	v_mfma_f32_16x16x32_bf16 v[58:61], v[174:177], v[206:209], v[58:61]
	v_mfma_f32_16x16x32_bf16 v[50:53], v[182:185], v[206:209], v[50:53]
	v_mfma_f32_16x16x32_bf16 v[42:45], v[174:177], v[214:217], v[42:45]
	v_mfma_f32_16x16x32_bf16 v[34:37], v[182:185], v[214:217], v[34:37]
	v_mfma_f32_16x16x32_bf16 v[26:29], v[174:177], v[222:225], v[26:29]
	v_mfma_f32_16x16x32_bf16 v[18:21], v[182:185], v[222:225], v[18:21]
	v_mfma_f32_16x16x32_bf16 v[10:13], v[174:177], v[230:233], v[10:13]
	v_mfma_f32_16x16x32_bf16 v[2:5], v[182:185], v[230:233], v[2:5]
	s_setprio 0
	s_barrier
; #define PG8_STAGE(bufoff, gbase, voff) do { _Pragma("unroll") for (int _i = 0; _i < 2; ++_i) \
;         __builtin_amdgcn_global_load_lds((const unsigned*)((const char*)(gbase) + (voff)[_i]), (LAS unsigned*)(lds + (bufoff) + ldsw + _i * 8192), 16, 0, 0); } while (0)
; #define PG8_LDA(dst, b, h) do { _Pragma("unroll") for (int m = 0; m < 4; ++m) _Pragma("unroll") for (int k = 0; k < 2; ++k) dst[m][k] = *(const LAS bf16x8*)(lds + PG8_SA(b, h) + aoff + m * 2048 + k * 1024); } while (0)
; #define PG8_LDB(dst, b, h) do { _Pragma("unroll") for (int n = 0; n < 2; ++n) _Pragma("unroll") for (int k = 0; k < 2; ++k) dst[n][k] = *(const LAS bf16x8*)(lds + PG8_SB(b, h) + boff + n * 2048 + k * 1024); } while (0)
; #define PG8_MMA(ai, bj, At, Bt) do { __builtin_amdgcn_s_setprio(1); _Pragma("unroll") for (int m = 0; m < 4; ++m) _Pragma("unroll") for (int n = 0; n < 2; ++n) _Pragma("unroll") for (int k = 0; k < 2; ++k) \
;         acc[ai][bj][m][n] = __builtin_amdgcn_mfma_f32_16x16x32_bf16(Bt[n][k], At[m][k], acc[ai][bj][m][n], 0, 0, 0); __builtin_amdgcn_s_setprio(0); } while (0)
; #define PG8_WAIT_V(n) asm volatile("s_waitcnt vmcnt(" #n ")" ::: "memory")
; #define PG8_WAIT_L(n) asm volatile("s_waitcnt lgkmcnt(" #n ")" ::: "memory")
; #define PG8_BAR __builtin_amdgcn_s_barrier()
; #define PG8_SCHED __builtin_amdgcn_sched_barrier(0)
; template <class Epi, bool ALIGN_EPI = PG8_ALIGN, bool SP2 = PG8_SP2>
; __device__ __forceinline__ void gemm_phase(LAS unsigned char* lds, const Gemm g, const StaticOrder& S, const Epi& E) {
;     ...
;             PG8_LDB(B0, 1, 0); PG8_LDB(B1, 1, 1); PG8_SCHED; PG8_LDA(At, 1, 0); PG8_STAGE(PG8_SA(0, 1), a2 + hstepA, voffA);
;             PG8_WAIT_V(8); PG8_WAIT_L(0); PG8_BAR; PG8_MMA(0, 0, At, B0); PG8_MMA(0, 1, At, B1); PG8_BAR; PG8_SCHED;
	s_add_i32 s48, 0, 0x18000
	v_add_u32_e32 v0, s48, v141
	s_add_i32 s49, 0, 0x1c000
	ds_read_b128 v[144:147], v0
	ds_read_b128 v[148:151], v0 offset:1024
	ds_read_b128 v[152:155], v0 offset:2048
	ds_read_b128 v[156:159], v0 offset:3072
	v_add_u32_e32 v0, s49, v141
	ds_read_b128 v[170:173], v0
	ds_read_b128 v[174:177], v0 offset:1024
	ds_read_b128 v[178:181], v0 offset:2048
	ds_read_b128 v[182:185], v0 offset:3072
	v_lshl_add_u64 v[166:167], s[24:25], 0, v[130:131]
	s_mov_b32 m0, s34
	s_nop 0
	global_load_lds_dwordx4 v[166:167], off
	s_mov_b32 m0, s35
	s_nop 0
	global_load_lds_dwordx4 v[194:195], off
	s_add_u32 s24, s24, 0x40000
	s_addc_u32 s25, s25, 0
	s_mov_b32 m0, s36
	v_lshl_add_u64 v[196:197], s[24:25], 0, v[130:131]
	ds_read_b128 v[186:189], v142 offset:32768
	ds_read_b128 v[206:209], v142 offset:33792
	ds_read_b128 v[210:213], v142 offset:34816
	ds_read_b128 v[214:217], v142 offset:35840
	ds_read_b128 v[218:221], v142 offset:36864
	ds_read_b128 v[222:225], v142 offset:37888
	ds_read_b128 v[226:229], v142 offset:38912
	ds_read_b128 v[230:233], v142 offset:39936
	global_load_lds_dwordx4 v[196:197], off
	v_lshl_add_u64 v[196:197], s[24:25], 0, v[132:133]
	s_mov_b32 m0, s37
	s_nop 0
	global_load_lds_dwordx4 v[196:197], off
	s_waitcnt vmcnt(8)
	s_waitcnt lgkmcnt(0)
	s_barrier
	s_setprio 1
	s_waitcnt lgkmcnt(0)
	v_mfma_f32_16x16x32_bf16 v[126:129], v[144:147], v[186:189], v[126:129]
	v_mfma_f32_16x16x32_bf16 v[118:121], v[152:155], v[186:189], v[118:121]
	v_mfma_f32_16x16x32_bf16 v[110:113], v[144:147], v[210:213], v[110:113]
	v_mfma_f32_16x16x32_bf16 v[102:105], v[152:155], v[210:213], v[102:105]
	v_mfma_f32_16x16x32_bf16 v[94:97], v[144:147], v[218:221], v[94:97]
	v_mfma_f32_16x16x32_bf16 v[86:89], v[152:155], v[218:221], v[86:89]
	v_mfma_f32_16x16x32_bf16 v[78:81], v[144:147], v[226:229], v[78:81]
	v_mfma_f32_16x16x32_bf16 v[70:73], v[152:155], v[226:229], v[70:73]
	v_mfma_f32_16x16x32_bf16 v[126:129], v[148:151], v[206:209], v[126:129]
	v_mfma_f32_16x16x32_bf16 v[118:121], v[156:159], v[206:209], v[118:121]
	v_mfma_f32_16x16x32_bf16 v[110:113], v[148:151], v[214:217], v[110:113]
	v_mfma_f32_16x16x32_bf16 v[102:105], v[156:159], v[214:217], v[102:105]
	v_mfma_f32_16x16x32_bf16 v[94:97], v[148:151], v[222:225], v[94:97]
	v_mfma_f32_16x16x32_bf16 v[86:89], v[156:159], v[222:225], v[86:89]
	v_mfma_f32_16x16x32_bf16 v[78:81], v[148:151], v[230:233], v[78:81]
	v_mfma_f32_16x16x32_bf16 v[70:73], v[156:159], v[230:233], v[70:73]
	s_setprio 0
	s_setprio 1
	v_mfma_f32_16x16x32_bf16 v[122:125], v[170:173], v[186:189], v[122:125]
	v_mfma_f32_16x16x32_bf16 v[114:117], v[178:181], v[186:189], v[114:117]
	v_mfma_f32_16x16x32_bf16 v[106:109], v[170:173], v[210:213], v[106:109]
	v_mfma_f32_16x16x32_bf16 v[98:101], v[178:181], v[210:213], v[98:101]
	v_mfma_f32_16x16x32_bf16 v[90:93], v[170:173], v[218:221], v[90:93]
	v_mfma_f32_16x16x32_bf16 v[82:85], v[178:181], v[218:221], v[82:85]
	v_mfma_f32_16x16x32_bf16 v[74:77], v[170:173], v[226:229], v[74:77]
	v_mfma_f32_16x16x32_bf16 v[66:69], v[178:181], v[226:229], v[66:69]
	v_mfma_f32_16x16x32_bf16 v[122:125], v[174:177], v[206:209], v[122:125]
	v_mfma_f32_16x16x32_bf16 v[114:117], v[182:185], v[206:209], v[114:117]
	v_mfma_f32_16x16x32_bf16 v[106:109], v[174:177], v[214:217], v[106:109]
	v_mfma_f32_16x16x32_bf16 v[98:101], v[182:185], v[214:217], v[98:101]
	v_mfma_f32_16x16x32_bf16 v[90:93], v[174:177], v[222:225], v[90:93]
	v_mfma_f32_16x16x32_bf16 v[82:85], v[182:185], v[222:225], v[82:85]
	v_mfma_f32_16x16x32_bf16 v[74:77], v[174:177], v[230:233], v[74:77]
	v_mfma_f32_16x16x32_bf16 v[66:69], v[182:185], v[230:233], v[66:69]
	s_setprio 0
	s_barrier
; #define PG8_STAGE(bufoff, gbase, voff) do { _Pragma("unroll") for (int _i = 0; _i < 2; ++_i) \
;         __builtin_amdgcn_global_load_lds((const unsigned*)((const char*)(gbase) + (voff)[_i]), (LAS unsigned*)(lds + (bufoff) + ldsw + _i * 8192), 16, 0, 0); } while (0)
; #define PG8_LDA(dst, b, h) do { _Pragma("unroll") for (int m = 0; m < 4; ++m) _Pragma("unroll") for (int k = 0; k < 2; ++k) dst[m][k] = *(const LAS bf16x8*)(lds + PG8_SA(b, h) + aoff + m * 2048 + k * 1024); } while (0)
; #define PG8_MMA(ai, bj, At, Bt) do { __builtin_amdgcn_s_setprio(1); _Pragma("unroll") for (int m = 0; m < 4; ++m) _Pragma("unroll") for (int n = 0; n < 2; ++n) _Pragma("unroll") for (int k = 0; k < 2; ++k) \
;         acc[ai][bj][m][n] = __builtin_amdgcn_mfma_f32_16x16x32_bf16(Bt[n][k], At[m][k], acc[ai][bj][m][n], 0, 0, 0); __builtin_amdgcn_s_setprio(0); } while (0)
; #define PG8_WAIT_V(n) asm volatile("s_waitcnt vmcnt(" #n ")" ::: "memory")
; #define PG8_WAIT_L(n) asm volatile("s_waitcnt lgkmcnt(" #n ")" ::: "memory")
; #define PG8_BAR __builtin_amdgcn_s_barrier()
; #define PG8_SCHED __builtin_amdgcn_sched_barrier(0)
; template <class Epi, bool ALIGN_EPI = PG8_ALIGN, bool SP2 = PG8_SP2>
; __device__ __forceinline__ void gemm_phase(LAS unsigned char* lds, const Gemm g, const StaticOrder& S, const Epi& E) {
;     ...
;             PG8_LDA(At, 1, 1); PG8_STAGE(PG8_SB(1, 0), b3, voffB); PG8_STAGE(PG8_SB(1, 1), b3 + hstepB, voffB); PG8_STAGE(PG8_SA(1, 0), a3, voffA);
;             PG8_WAIT_V(8); PG8_WAIT_L(0); PG8_BAR; PG8_MMA(1, 0, At, B0); PG8_MMA(1, 1, At, B1); PG8_BAR; PG8_SCHED;
	s_add_i32 s24, s48, s33
	v_lshl_add_u64 v[160:161], v[160:161], 0, s[50:51]
	s_mov_b32 m0, s24
	ds_read_b128 v[186:189], v142 offset:49152
	ds_read_b128 v[206:209], v142 offset:50176
	ds_read_b128 v[210:213], v142 offset:51200
	ds_read_b128 v[214:217], v142 offset:52224
	ds_read_b128 v[218:221], v142 offset:53248
	ds_read_b128 v[222:225], v142 offset:54272
	ds_read_b128 v[226:229], v142 offset:55296
	ds_read_b128 v[230:233], v142 offset:56320
	global_load_lds_dwordx4 v[160:161], off
	s_add_i32 m0, s24, 0x2000
	s_add_u32 s22, s22, 0x40080
	v_lshl_add_u64 v[160:161], v[164:165], 0, s[50:51]
	s_addc_u32 s23, s23, 0
	s_add_i32 s24, s49, s33
	global_load_lds_dwordx4 v[160:161], off
	v_lshl_add_u64 v[160:161], s[22:23], 0, v[130:131]
	s_mov_b32 m0, s24
	s_nop 0
	global_load_lds_dwordx4 v[160:161], off
	v_lshl_add_u64 v[160:161], s[22:23], 0, v[132:133]
	s_add_i32 m0, s24, 0x2000
	s_nop 0
	global_load_lds_dwordx4 v[160:161], off
	v_lshl_add_u64 v[160:161], v[166:167], 0, s[50:51]
	s_mov_b32 m0, s40
	s_nop 0
	global_load_lds_dwordx4 v[160:161], off
	v_lshl_add_u64 v[160:161], v[194:195], 0, s[50:51]
	s_mov_b32 m0, s41
	s_nop 0
	global_load_lds_dwordx4 v[160:161], off
	s_waitcnt vmcnt(8)
	s_waitcnt lgkmcnt(0)
	s_barrier
	s_setprio 1
	s_waitcnt lgkmcnt(0)
	v_mfma_f32_16x16x32_bf16 v[62:65], v[144:147], v[186:189], v[62:65]
	v_mfma_f32_16x16x32_bf16 v[54:57], v[152:155], v[186:189], v[54:57]
	v_mfma_f32_16x16x32_bf16 v[46:49], v[144:147], v[210:213], v[46:49]
	v_mfma_f32_16x16x32_bf16 v[38:41], v[152:155], v[210:213], v[38:41]
	v_mfma_f32_16x16x32_bf16 v[30:33], v[144:147], v[218:221], v[30:33]
	v_mfma_f32_16x16x32_bf16 v[22:25], v[152:155], v[218:221], v[22:25]
	v_mfma_f32_16x16x32_bf16 v[14:17], v[144:147], v[226:229], v[14:17]
	v_mfma_f32_16x16x32_bf16 v[6:9], v[152:155], v[226:229], v[6:9]
	v_mfma_f32_16x16x32_bf16 v[62:65], v[148:151], v[206:209], v[62:65]
	v_mfma_f32_16x16x32_bf16 v[54:57], v[156:159], v[206:209], v[54:57]
	v_mfma_f32_16x16x32_bf16 v[46:49], v[148:151], v[214:217], v[46:49]
	v_mfma_f32_16x16x32_bf16 v[38:41], v[156:159], v[214:217], v[38:41]
	v_mfma_f32_16x16x32_bf16 v[30:33], v[148:151], v[222:225], v[30:33]
	v_mfma_f32_16x16x32_bf16 v[22:25], v[156:159], v[222:225], v[22:25]
	v_mfma_f32_16x16x32_bf16 v[14:17], v[148:151], v[230:233], v[14:17]
	v_mfma_f32_16x16x32_bf16 v[6:9], v[156:159], v[230:233], v[6:9]
	s_setprio 0
	s_setprio 1
	v_mfma_f32_16x16x32_bf16 v[58:61], v[170:173], v[186:189], v[58:61]
	v_mfma_f32_16x16x32_bf16 v[50:53], v[178:181], v[186:189], v[50:53]
	v_mfma_f32_16x16x32_bf16 v[42:45], v[170:173], v[210:213], v[42:45]
	v_mfma_f32_16x16x32_bf16 v[34:37], v[178:181], v[210:213], v[34:37]
	v_mfma_f32_16x16x32_bf16 v[26:29], v[170:173], v[218:221], v[26:29]
	v_mfma_f32_16x16x32_bf16 v[18:21], v[178:181], v[218:221], v[18:21]
	v_mfma_f32_16x16x32_bf16 v[10:13], v[170:173], v[226:229], v[10:13]
	v_mfma_f32_16x16x32_bf16 v[2:5], v[178:181], v[226:229], v[2:5]
	v_mfma_f32_16x16x32_bf16 v[58:61], v[174:177], v[206:209], v[58:61]
	v_mfma_f32_16x16x32_bf16 v[50:53], v[182:185], v[206:209], v[50:53]
	v_mfma_f32_16x16x32_bf16 v[42:45], v[174:177], v[214:217], v[42:45]
	v_mfma_f32_16x16x32_bf16 v[34:37], v[182:185], v[214:217], v[34:37]
	v_mfma_f32_16x16x32_bf16 v[26:29], v[174:177], v[222:225], v[26:29]
	v_mfma_f32_16x16x32_bf16 v[18:21], v[182:185], v[222:225], v[18:21]
	v_mfma_f32_16x16x32_bf16 v[10:13], v[174:177], v[230:233], v[10:13]
	v_mfma_f32_16x16x32_bf16 v[2:5], v[182:185], v[230:233], v[2:5]
	s_setprio 0
	s_barrier
	s_add_i32 s47, s47, 2
	s_add_u32 s20, s20, 0x100
	s_addc_u32 s21, s21, 0
	s_add_u32 s45, s45, 0x100
	s_addc_u32 s46, s46, 0
	s_cmp_gt_u32 s47, 13
	s_branch .LBB0_611
